# P7: merge-gate tile touched line-by-line during K segment 0 so the EpiRatio / EpiMerge2 gate loads hit cache
# baseline (speedup 1.0000x reference)
; #define PG8_WAIT_V(n) asm volatile("s_waitcnt vmcnt(" #n ")" ::: "memory")
; #define PG8_BAR __builtin_amdgcn_s_barrier()
; #define PG8_WAIT_V(n) asm volatile("s_waitcnt vmcnt(" #n ")" ::: "memory")
; #define PG8_BAR __builtin_amdgcn_s_barrier()
; template <class EpiMid, class EpiEnd>
; __device__ __forceinline__ void gemm_phase2(LAS unsigned char* lds, const Gemm g0, const Gemm g1, const StaticOrder& S, const EpiMid& Emid, const EpiEnd& Eend) {
;     const int tid = threadIdx.x, wid = __builtin_amdgcn_readfirstlane(tid >> 6), lane = tid & 63, wr = wid >> 2, wc = wid & 3, fr = lane & 15, fq = lane >> 4;
;     unsigned rA2[2], rB2[2], cb2[2];
; #pragma unroll
;     for (int i = 0; i < 2; ++i) { int R, C; stage_rc(tid * 16 + i * 8192, R, C); const int Rb = (R & ~31) + perm32(R & 31); rA2[i] = (unsigned)R * 2u; rB2[i] = (unsigned)Rb * 2u; cb2[i] = (unsigned)C * 2u; }
;     const size_t kstep = (size_t)(BK * 2);
;     const unsigned K0 = (unsigned)g0.K, K1 = (unsigned)g1.K;
;     const size_t hstep0 = (size_t)HALF * g0.K * 2, hstep1 = (size_t)HALF * g1.K * 2;
;     const unsigned ldsw = (unsigned)wid * 1024u;
;     const int aoff = lds_byte(wr * 64 + fr, fq * 8), boff = lds_byte(wc * 32 + fr, fq * 8);
;     ...
;     Unit cur, nxt; int ui = 0;
;     if (!S.next(0, cur)) return;
;     f32x4 acc[2][2][4][2];
; #pragma unroll
;     for (int a = 0; a < 2; ++a)
; #pragma unroll
;         for (int b = 0; b < 2; ++b)
; #pragma unroll
;             for (int m = 0; m < 4; ++m)
; #pragma unroll
;                 for (int n = 0; n < 2; ++n) acc[a][b][m][n] = (f32x4){0.f, 0.f, 0.f, 0.f};
;     bf16x8 At[4][2], B0[2][2], B1[2][2];
;     const char* cA = (const char*)g0.A + (size_t)cur.pm * 2 * hstep0; const char* cB = (const char*)g0.Bt + (size_t)cur.pn * 2 * hstep0;
;     PG8_STAGE2(PG8_SB(0, 0), cB, rB2, K0); PG8_STAGE2(PG8_SA(0, 0), cA, rA2, K0);
;     PG8_STAGE2(PG8_SB(0, 1), cB + hstep0, rB2, K0); PG8_STAGE2(PG8_SA(0, 1), cA + hstep0, rA2, K0);
;     if (wr == 1) PG8_BAR;
;     PG8_WAIT_V(4); PG8_BAR;
;     PG8_STAGE2(PG8_SB(1, 0), cB + kstep, rB2, K0); PG8_STAGE2(PG8_SA(1, 0), cA + kstep, rA2, K0); PG8_STAGE2(PG8_SB(1, 1), cB + hstep0 + kstep, rB2, K0);
;     PG8_WAIT_V(6); PG8_BAR;
.LBB0_759:
	s_ashr_i32 s2, s5, 3
	s_add_u32 s34, s88, 0x1800000
	s_addc_u32 s35, s89, 0
	s_add_i32 s2, s4, s2
	s_ashr_i32 s4, s2, 31
	s_lshr_b32 s4, s4, 28
	s_add_i32 s4, s2, s4
	s_ashr_i32 s5, s4, 4
	s_and_b32 s4, s4, -16
	s_sub_i32 s4, s2, s4
	s_bfe_i32 s2, s4, 0x80000
	s_waitcnt vmcnt(0)
	v_lshlrev_b32_e32 v0, 4, v212
	v_and_b32_e32 v1, 32, v212
	s_bfe_u32 s2, s2, 0x2000d
	v_bitop3_b32 v12, v0, v1, 48 bitop3:0x6c
	v_lshrrev_b32_e32 v1, 1, v212
	v_lshrrev_b32_e32 v3, 5, v212
	s_add_i32 s9, s4, s2
	v_and_b32_e32 v1, 24, v1
	v_and_b32_e32 v3, 4, v3
	v_bfe_u32 v4, v212, 2, 2
	s_bfe_i32 s2, s9, 0x80000
	s_and_b32 s9, s9, 0xfc
	v_bfe_u32 v2, v212, 2, 4
	v_or3_b32 v1, v3, v4, v1
	v_lshrrev_b32_e32 v3, 3, v212
	s_movk_i32 s3, 0x70
	s_sub_i32 s4, s4, s9
	v_and_or_b32 v14, v3, s3, v2
	s_movk_i32 s3, 0x60
	v_add_u32_e32 v0, 0x2000, v0
	s_lshl_b32 s5, s5, 2
	s_sext_i32_i8 s4, s4
	v_and_or_b32 v15, v3, s3, v1
	v_lshrrev_b32_e32 v0, 7, v0
	s_movk_i32 s3, 0xf0
	s_add_i32 s18, s5, s4
	s_lshr_b32 s8, s30, 6
	v_and_or_b32 v16, v0, s3, v2
	s_movk_i32 s3, 0xe0
	s_sext_i32_i16 s2, s2
	s_ashr_i32 s19, s18, 31
	v_and_or_b32 v17, v0, s3, v1
	s_lshr_b32 s3, s30, 8
	s_lshl_b32 s33, s8, 10
	s_lshr_b32 s2, s2, 2
	s_lshl_b64 s[4:5], s[18:19], 19
	s_lshl_b32 s100, s18, 20
	s_add_u32 s96, s94, s100
	s_addc_u32 s97, s95, 0
	s_lshl_b32 s100, s2, 9
	s_add_u32 s96, s96, s100
	s_addc_u32 s97, s97, 0
	v_and_b32_e32 v240, 15, v212
	v_lshlrev_b32_e32 v240, 12, v240
	v_bfe_u32 v241, v212, 4, 4
	v_lshl_add_u32 v240, v241, 5, v240
	v_lshrrev_b32_e32 v241, 8, v212
	v_lshl_add_u32 v240, v241, 11, v240
	v_readlane_b32 s10, v254, 23
	v_readlane_b32 s11, v254, 24
	s_add_u32 s20, s10, s4
	s_addc_u32 s21, s11, s5
	s_bfe_i64 s[4:5], s[2:3], 0x100000
	s_lshl_b64 s[4:5], s[4:5], 19
	v_and_b32_e32 v13, 64, v212
	s_add_u32 s24, s34, s4
	v_or_b32_e32 v154, v12, v13
	s_addc_u32 s25, s35, s5
	s_add_i32 s36, s33, 0
	v_lshl_or_b32 v0, v15, 11, v154
	s_add_i32 m0, s36, 0x10000
	v_lshl_or_b32 v2, v17, 11, v154
	global_load_lds_dwordx4 v0, s[24:25]
	s_add_i32 m0, s36, 0x12000
	v_lshl_or_b32 v4, v14, 11, v154
	global_load_lds_dwordx4 v2, s[24:25]
	s_mov_b32 m0, s36
	s_add_i32 s37, s36, 0x2000
	global_load_lds_dwordx4 v4, s[20:21]
	v_lshl_or_b32 v18, v16, 11, v154
	s_mov_b32 m0, s37
	s_add_u32 s4, s24, 0x40000
	global_load_lds_dwordx4 v18, s[20:21]
	s_addc_u32 s5, s25, 0
	s_add_i32 m0, s36, 0x14000
	v_mov_b32_e32 v1, 0
	global_load_lds_dwordx4 v0, s[4:5]
	s_add_i32 m0, s36, 0x16000
	v_mov_b32_e32 v3, v1
	global_load_lds_dwordx4 v2, s[4:5]
	s_add_u32 s4, s20, 0x40000
	s_addc_u32 s5, s21, 0
	s_add_i32 s38, s36, 0x4000
	s_mov_b32 m0, s38
	s_add_i32 s39, s36, 0x6000
	global_load_lds_dwordx4 v4, s[4:5]
	s_mov_b32 m0, s39
	v_mov_b32_e32 v5, v1
	global_load_lds_dwordx4 v18, s[4:5]
	v_mov_b32_e32 v19, v1
	v_lshl_add_u64 v[10:11], s[24:25], 0, v[0:1]
	s_mov_b32 s40, 0
	v_lshl_add_u64 v[8:9], s[24:25], 0, v[2:3]
	v_lshl_add_u64 v[6:7], s[20:21], 0, v[4:5]
	s_cmp_lg_u32 s3, 1
	v_lshl_add_u64 v[4:5], s[20:21], 0, v[18:19]
	s_cbranch_scc1 .LBB0_761
	s_barrier

; #define PG8_LDA(dst, b, h) do { _Pragma("unroll") for (int m = 0; m < 4; ++m) _Pragma("unroll") for (int k = 0; k < 2; ++k) dst[m][k] = *(const LAS bf16x8*)(lds + PG8_SA(b, h) + aoff + m * 2048 + k * 1024); } while (0)
; #define PG8_LDB(dst, b, h) do { _Pragma("unroll") for (int n = 0; n < 2; ++n) _Pragma("unroll") for (int k = 0; k < 2; ++k) dst[n][k] = *(const LAS bf16x8*)(lds + PG8_SB(b, h) + boff + n * 2048 + k * 1024); } while (0)
; #define PG8_MMA(ai, bj, At, Bt) do { __builtin_amdgcn_s_setprio(1); _Pragma("unroll") for (int m = 0; m < 4; ++m) _Pragma("unroll") for (int n = 0; n < 2; ++n) _Pragma("unroll") for (int k = 0; k < 2; ++k) \
;         acc[ai][bj][m][n] = __builtin_amdgcn_mfma_f32_16x16x32_bf16(Bt[n][k], At[m][k], acc[ai][bj][m][n], 0, 0, 0); __builtin_amdgcn_s_setprio(0); } while (0)
; #define PG8_WAIT_L(n) asm volatile("s_waitcnt lgkmcnt(" #n ")" ::: "memory")
; #define PG8_BAR __builtin_amdgcn_s_barrier()
; #define PG8_SCHED __builtin_amdgcn_sched_barrier(0)
; #define PG8_LDA(dst, b, h) do { _Pragma("unroll") for (int m = 0; m < 4; ++m) _Pragma("unroll") for (int k = 0; k < 2; ++k) dst[m][k] = *(const LAS bf16x8*)(lds + PG8_SA(b, h) + aoff + m * 2048 + k * 1024); } while (0)
; template <class EpiMid, class EpiEnd>
; __device__ __forceinline__ void gemm_phase2(LAS unsigned char* lds, const Gemm g0, const Gemm g1, const StaticOrder& S, const EpiMid& Emid, const EpiEnd& Eend) {
;     ...
;                 const bool last = (t == nt - 2);
;                 const char* a1 = cA + (size_t)(t + 1) * kstep;
;                 const char* a2 = last ? nA : cA + (size_t)(t + 2) * kstep; const char* b2 = last ? nB : cB + (size_t)(t + 2) * kstep;
;                 const char* a3 = a2 + kstep; const char* b3 = b2 + kstep;
;                 const size_t h2 = last ? hsn : hs;
;                 const unsigned K2 = last ? Kn : Kc;
;                 PG8_LDB(B0, 0, 0); PG8_SCHED; PG8_LDA(At, 0, 0); PG8_STAGE2(PG8_SA(1, 1), a1 + hs, rA2, Kc);
;                 PG8_WAIT_L(8); PG8_BAR; PG8_WAIT_L(0); PG8_MMA(0, 0, At, B0); PG8_BAR; PG8_SCHED;
;                 PG8_LDB(B1, 0, 1); PG8_STAGE2(PG8_SB(0, 0), b2, rB2, K2);
;                 PG8_BAR; PG8_WAIT_L(0); PG8_MMA(0, 1, At, B1); PG8_BAR;
;                 PG8_LDA(At, 0, 1); PG8_STAGE2(PG8_SA(0, 0), a2, rA2, K2);
;                 PG8_BAR; PG8_WAIT_L(0); PG8_MMA(1, 0, At, B0); PG8_BAR; PG8_SCHED;
.LBB0_772:
	s_cmp_eq_u32 s62, s24
	s_cselect_b64 s[64:65], -1, 0
	s_add_i32 s54, s54, 2
	s_add_u32 s26, s20, s24
	v_add_u32_e32 v0, s48, v159
	s_addc_u32 s27, s21, s25
	ds_read_b128 v[134:137], v0
	ds_read_b128 v[138:141], v0 offset:1024
	ds_read_b128 v[142:145], v0 offset:2048
	ds_read_b128 v[146:149], v0 offset:3072
	s_add_u32 s28, s26, 0x100
	s_addc_u32 s29, s27, 0
	s_and_b64 s[26:27], s[64:65], exec
	s_cselect_b32 s27, s56, s29
	s_cselect_b32 s26, s57, s28
	s_cselect_b32 s63, 0, 0
	s_cselect_b32 s66, s55, s53
	s_add_u32 s67, s60, s24
	s_addc_u32 s68, s61, s25
	s_and_b64 s[28:29], s[64:65], exec
	s_cselect_b32 s29, s58, s68
	s_cselect_b32 s28, s59, s67
	v_lshl_add_u64 v[150:151], v[2:3], 0, s[24:25]
	s_add_i32 m0, s36, 0xc000
	ds_read_b128 v[170:173], v165
	ds_read_b128 v[174:177], v165 offset:1024
	ds_read_b128 v[178:181], v165 offset:2048
	ds_read_b128 v[182:185], v165 offset:3072
	ds_read_b128 v[186:189], v165 offset:4096
	ds_read_b128 v[190:193], v165 offset:5120
	ds_read_b128 v[194:197], v165 offset:6144
	ds_read_b128 v[198:201], v165 offset:7168
	global_load_lds_dwordx4 v[150:151], off
	v_lshl_add_u64 v[150:151], v[132:133], 0, s[24:25]
	s_add_i32 m0, s36, 0xe000
	s_nop 0
	global_load_lds_dwordx4 v[150:151], off
	s_waitcnt lgkmcnt(8)
	s_barrier
	s_waitcnt lgkmcnt(0)
	s_setprio 1
	s_waitcnt lgkmcnt(0)
	v_mfma_f32_16x16x32_bf16 v[128:131], v[134:137], v[170:173], v[128:131]
	v_mfma_f32_16x16x32_bf16 v[124:127], v[142:145], v[170:173], v[124:127]
	v_mfma_f32_16x16x32_bf16 v[120:123], v[134:137], v[178:181], v[120:123]
	v_mfma_f32_16x16x32_bf16 v[116:119], v[142:145], v[178:181], v[116:119]
	v_mfma_f32_16x16x32_bf16 v[112:115], v[134:137], v[186:189], v[112:115]
	v_mfma_f32_16x16x32_bf16 v[108:111], v[142:145], v[186:189], v[108:111]
	v_mfma_f32_16x16x32_bf16 v[104:107], v[134:137], v[194:197], v[104:107]
	v_mfma_f32_16x16x32_bf16 v[100:103], v[142:145], v[194:197], v[100:103]
	v_mfma_f32_16x16x32_bf16 v[128:131], v[138:141], v[174:177], v[128:131]
	v_mfma_f32_16x16x32_bf16 v[124:127], v[146:149], v[174:177], v[124:127]
	v_mfma_f32_16x16x32_bf16 v[120:123], v[138:141], v[182:185], v[120:123]
	v_mfma_f32_16x16x32_bf16 v[116:119], v[146:149], v[182:185], v[116:119]
	v_mfma_f32_16x16x32_bf16 v[112:115], v[138:141], v[190:193], v[112:115]
	v_mfma_f32_16x16x32_bf16 v[108:111], v[146:149], v[190:193], v[108:111]
	v_mfma_f32_16x16x32_bf16 v[104:107], v[138:141], v[198:201], v[104:107]
	v_mfma_f32_16x16x32_bf16 v[100:103], v[146:149], v[198:201], v[100:103]
	s_setprio 0
	s_barrier
	s_xor_b64 s[64:65], s[22:23], s[64:65]
	s_and_b64 s[64:65], s[64:65], exec
	v_add_u32_e32 v0, s49, v159
	s_cselect_b32 s64, 10, 9
	s_add_i32 s65, s48, s33
	ds_read_b128 v[202:205], v0
	ds_read_b128 v[206:209], v0 offset:1024
	ds_read_b128 v[214:217], v0 offset:2048
	ds_read_b128 v[218:221], v0 offset:3072
	v_lshl_or_b32 v0, v156, s64, v154
	s_mov_b32 m0, s65
	v_lshl_or_b32 v150, v158, s64, v154
	global_load_lds_dwordx4 v0, s[28:29]
	s_add_i32 m0, s65, 0x2000
	v_mov_b32_e32 v151, v1
	global_load_lds_dwordx4 v150, s[28:29]
	s_barrier
	s_waitcnt lgkmcnt(0)
	v_lshl_add_u64 v[210:211], s[28:29], 0, v[0:1]
	v_lshl_add_u64 v[222:223], s[28:29], 0, v[150:151]
	s_setprio 1
	s_waitcnt lgkmcnt(0)
	v_mfma_f32_16x16x32_bf16 v[96:99], v[202:205], v[170:173], v[96:99]
	v_mfma_f32_16x16x32_bf16 v[92:95], v[214:217], v[170:173], v[92:95]
	v_mfma_f32_16x16x32_bf16 v[88:91], v[202:205], v[178:181], v[88:91]
	v_mfma_f32_16x16x32_bf16 v[84:87], v[214:217], v[178:181], v[84:87]
	v_mfma_f32_16x16x32_bf16 v[80:83], v[202:205], v[186:189], v[80:83]
	v_mfma_f32_16x16x32_bf16 v[76:79], v[214:217], v[186:189], v[76:79]
	v_mfma_f32_16x16x32_bf16 v[72:75], v[202:205], v[194:197], v[72:75]
	v_mfma_f32_16x16x32_bf16 v[68:71], v[214:217], v[194:197], v[68:71]
	v_mfma_f32_16x16x32_bf16 v[96:99], v[206:209], v[174:177], v[96:99]
	v_mfma_f32_16x16x32_bf16 v[92:95], v[218:221], v[174:177], v[92:95]
	v_mfma_f32_16x16x32_bf16 v[88:91], v[206:209], v[182:185], v[88:91]
	v_mfma_f32_16x16x32_bf16 v[84:87], v[218:221], v[182:185], v[84:87]
	v_mfma_f32_16x16x32_bf16 v[80:83], v[206:209], v[190:193], v[80:83]
	v_mfma_f32_16x16x32_bf16 v[76:79], v[218:221], v[190:193], v[76:79]
	v_mfma_f32_16x16x32_bf16 v[72:75], v[206:209], v[198:201], v[72:75]
	v_mfma_f32_16x16x32_bf16 v[68:71], v[218:221], v[198:201], v[68:71]
	s_setprio 0
	s_mov_b32 m0, s36
	v_lshl_or_b32 v224, v155, s64, v154
	s_barrier
	ds_read_b128 v[170:173], v165 offset:16384
	ds_read_b128 v[174:177], v165 offset:17408
	ds_read_b128 v[178:181], v165 offset:18432
	ds_read_b128 v[182:185], v165 offset:19456
	ds_read_b128 v[186:189], v165 offset:20480
	ds_read_b128 v[190:193], v165 offset:21504
	ds_read_b128 v[194:197], v165 offset:22528
	ds_read_b128 v[198:201], v165 offset:23552
	global_load_lds_dwordx4 v224, s[26:27]
	v_lshl_or_b32 v226, v157, s64, v154
	s_mov_b32 m0, s37
	v_mov_b32_e32 v225, v1
	global_load_lds_dwordx4 v226, s[26:27]
	s_barrier
	s_waitcnt lgkmcnt(0)
	v_mov_b32_e32 v227, v1
	v_lshl_add_u64 v[228:229], s[26:27], 0, v[224:225]
	v_lshl_add_u64 v[230:231], s[26:27], 0, v[226:227]
	s_setprio 1
	s_waitcnt lgkmcnt(0)
	v_mfma_f32_16x16x32_bf16 v[64:67], v[134:137], v[170:173], v[64:67]
	v_mfma_f32_16x16x32_bf16 v[60:63], v[142:145], v[170:173], v[60:63]
	v_mfma_f32_16x16x32_bf16 v[56:59], v[134:137], v[178:181], v[56:59]
	v_mfma_f32_16x16x32_bf16 v[52:55], v[142:145], v[178:181], v[52:55]
	v_mfma_f32_16x16x32_bf16 v[48:51], v[134:137], v[186:189], v[48:51]
	v_mfma_f32_16x16x32_bf16 v[44:47], v[142:145], v[186:189], v[44:47]
	v_mfma_f32_16x16x32_bf16 v[40:43], v[134:137], v[194:197], v[40:43]
	v_mfma_f32_16x16x32_bf16 v[36:39], v[142:145], v[194:197], v[36:39]
	v_mfma_f32_16x16x32_bf16 v[64:67], v[138:141], v[174:177], v[64:67]
	v_mfma_f32_16x16x32_bf16 v[60:63], v[146:149], v[174:177], v[60:63]
	v_mfma_f32_16x16x32_bf16 v[56:59], v[138:141], v[182:185], v[56:59]
	v_mfma_f32_16x16x32_bf16 v[52:55], v[146:149], v[182:185], v[52:55]
	v_mfma_f32_16x16x32_bf16 v[48:51], v[138:141], v[190:193], v[48:51]
	v_mfma_f32_16x16x32_bf16 v[44:47], v[146:149], v[190:193], v[44:47]
	v_mfma_f32_16x16x32_bf16 v[40:43], v[138:141], v[198:201], v[40:43]
	v_mfma_f32_16x16x32_bf16 v[36:39], v[146:149], v[198:201], v[36:39]
	s_setprio 0
	s_barrier
; #define PG8_LDA(dst, b, h) do { _Pragma("unroll") for (int m = 0; m < 4; ++m) _Pragma("unroll") for (int k = 0; k < 2; ++k) dst[m][k] = *(const LAS bf16x8*)(lds + PG8_SA(b, h) + aoff + m * 2048 + k * 1024); } while (0)
; #define PG8_LDB(dst, b, h) do { _Pragma("unroll") for (int n = 0; n < 2; ++n) _Pragma("unroll") for (int k = 0; k < 2; ++k) dst[n][k] = *(const LAS bf16x8*)(lds + PG8_SB(b, h) + boff + n * 2048 + k * 1024); } while (0)
; #define PG8_MMA(ai, bj, At, Bt) do { __builtin_amdgcn_s_setprio(1); _Pragma("unroll") for (int m = 0; m < 4; ++m) _Pragma("unroll") for (int n = 0; n < 2; ++n) _Pragma("unroll") for (int k = 0; k < 2; ++k) \
;         acc[ai][bj][m][n] = __builtin_amdgcn_mfma_f32_16x16x32_bf16(Bt[n][k], At[m][k], acc[ai][bj][m][n], 0, 0, 0); __builtin_amdgcn_s_setprio(0); } while (0)
; #define PG8_WAIT_V(n) asm volatile("s_waitcnt vmcnt(" #n ")" ::: "memory")
; #define PG8_WAIT_L(n) asm volatile("s_waitcnt lgkmcnt(" #n ")" ::: "memory")
; #define PG8_BAR __builtin_amdgcn_s_barrier()
; #define PG8_SCHED __builtin_amdgcn_sched_barrier(0)
; #define PG8_STAGE2(bufoff, gbase, r2, Ksel) do { \
;         __builtin_amdgcn_global_load_lds((const unsigned*)((const char*)(gbase) + ((r2)[0] * (Ksel) + cb2[0])), (LAS unsigned*)(lds + (bufoff) + ldsw), 16, 0, 0); \
;         __builtin_amdgcn_global_load_lds((const unsigned*)((const char*)(gbase) + ((r2)[1] * (Ksel) + cb2[1])), (LAS unsigned*)(lds + (bufoff) + ldsw + 8192), 16, 0, 0); } while (0)
; #define PG8_LDA(dst, b, h) do { _Pragma("unroll") for (int m = 0; m < 4; ++m) _Pragma("unroll") for (int k = 0; k < 2; ++k) dst[m][k] = *(const LAS bf16x8*)(lds + PG8_SA(b, h) + aoff + m * 2048 + k * 1024); } while (0)
; template <class EpiMid, class EpiEnd>
; __device__ __forceinline__ void gemm_phase2(LAS unsigned char* lds, const Gemm g0, const Gemm g1, const StaticOrder& S, const EpiMid& Emid, const EpiEnd& Eend) {
;     ...
;                 PG8_STAGE2(PG8_SB(0, 1), b2 + h2, rB2, K2);
;                 PG8_WAIT_V(6); PG8_BAR; PG8_MMA(1, 1, At, B1); PG8_BAR;
;                 PG8_LDB(B0, 1, 0); PG8_SCHED; PG8_LDA(At, 1, 0); PG8_STAGE2(PG8_SA(0, 1), a2 + h2, rA2, K2);
;                 PG8_WAIT_L(8); PG8_BAR; PG8_WAIT_L(0); PG8_MMA(0, 0, At, B0); PG8_BAR; PG8_SCHED;
;                 PG8_LDB(B1, 1, 1); PG8_STAGE2(PG8_SB(1, 0), b3, rB2, K2);
;                 PG8_BAR; PG8_WAIT_L(0); PG8_MMA(0, 1, At, B1); PG8_BAR;
	s_add_u32 s28, s28, s66
	s_addc_u32 s29, s29, s63
	s_add_i32 s64, s49, s33
	s_mov_b32 m0, s64
	v_lshl_add_u64 v[232:233], s[28:29], 0, v[0:1]
	global_load_lds_dwordx4 v0, s[28:29]
	s_add_i32 m0, s64, 0x2000
	s_nop 0
	global_load_lds_dwordx4 v150, s[28:29]
	s_waitcnt vmcnt(6)
	global_load_dword v242, v240, s[96:97]
	v_add_u32_e32 v240, 0x10000, v240
	v_lshl_add_u64 v[150:151], s[28:29], 0, v[150:151]
	s_barrier
	s_setprio 1
	v_mfma_f32_16x16x32_bf16 v[32:35], v[202:205], v[170:173], v[32:35]
	v_mfma_f32_16x16x32_bf16 v[28:31], v[214:217], v[170:173], v[28:31]
	v_mfma_f32_16x16x32_bf16 v[24:27], v[202:205], v[178:181], v[24:27]
	v_mfma_f32_16x16x32_bf16 v[20:23], v[214:217], v[178:181], v[20:23]
	v_mfma_f32_16x16x32_bf16 v[16:19], v[202:205], v[186:189], v[16:19]
	v_mfma_f32_16x16x32_bf16 v[12:15], v[214:217], v[186:189], v[12:15]
	v_mfma_f32_16x16x32_bf16 v[8:11], v[202:205], v[194:197], v[8:11]
	v_mfma_f32_16x16x32_bf16 v[4:7], v[214:217], v[194:197], v[4:7]
	v_mfma_f32_16x16x32_bf16 v[32:35], v[206:209], v[174:177], v[32:35]
	v_mfma_f32_16x16x32_bf16 v[28:31], v[218:221], v[174:177], v[28:31]
	v_mfma_f32_16x16x32_bf16 v[24:27], v[206:209], v[182:185], v[24:27]
	v_mfma_f32_16x16x32_bf16 v[20:23], v[218:221], v[182:185], v[20:23]
	v_mfma_f32_16x16x32_bf16 v[16:19], v[206:209], v[190:193], v[16:19]
	v_mfma_f32_16x16x32_bf16 v[12:15], v[218:221], v[190:193], v[12:15]
	v_mfma_f32_16x16x32_bf16 v[8:11], v[206:209], v[198:201], v[8:11]
	v_mfma_f32_16x16x32_bf16 v[4:7], v[218:221], v[198:201], v[4:7]
	s_setprio 0
	s_add_i32 s28, 0, 0x18000
	v_add_u32_e32 v0, s28, v159
	s_barrier
	ds_read_b128 v[134:137], v0
	ds_read_b128 v[138:141], v0 offset:1024
	ds_read_b128 v[142:145], v0 offset:2048
	ds_read_b128 v[146:149], v0 offset:3072
	s_add_u32 s26, s26, s66
	s_addc_u32 s27, s27, s63
	s_mov_b32 m0, s38
	ds_read_b128 v[170:173], v165 offset:32768
	ds_read_b128 v[174:177], v165 offset:33792
	ds_read_b128 v[178:181], v165 offset:34816
	ds_read_b128 v[182:185], v165 offset:35840
	ds_read_b128 v[186:189], v165 offset:36864
	ds_read_b128 v[190:193], v165 offset:37888
	ds_read_b128 v[194:197], v165 offset:38912
	ds_read_b128 v[198:201], v165 offset:39936
	global_load_lds_dwordx4 v224, s[26:27]
	s_mov_b32 m0, s39
	s_nop 0
	global_load_lds_dwordx4 v226, s[26:27]
	s_waitcnt lgkmcnt(8)
	s_barrier
	s_waitcnt lgkmcnt(0)
	s_setprio 1
	s_waitcnt lgkmcnt(0)
	v_mfma_f32_16x16x32_bf16 v[128:131], v[134:137], v[170:173], v[128:131]
	v_mfma_f32_16x16x32_bf16 v[124:127], v[142:145], v[170:173], v[124:127]
	v_mfma_f32_16x16x32_bf16 v[120:123], v[134:137], v[178:181], v[120:123]
	v_mfma_f32_16x16x32_bf16 v[116:119], v[142:145], v[178:181], v[116:119]
	v_mfma_f32_16x16x32_bf16 v[112:115], v[134:137], v[186:189], v[112:115]
	v_mfma_f32_16x16x32_bf16 v[108:111], v[142:145], v[186:189], v[108:111]
	v_mfma_f32_16x16x32_bf16 v[104:107], v[134:137], v[194:197], v[104:107]
	v_mfma_f32_16x16x32_bf16 v[100:103], v[142:145], v[194:197], v[100:103]
	v_mfma_f32_16x16x32_bf16 v[128:131], v[138:141], v[174:177], v[128:131]
	v_mfma_f32_16x16x32_bf16 v[124:127], v[146:149], v[174:177], v[124:127]
	v_mfma_f32_16x16x32_bf16 v[120:123], v[138:141], v[182:185], v[120:123]
	v_mfma_f32_16x16x32_bf16 v[116:119], v[146:149], v[182:185], v[116:119]
	v_mfma_f32_16x16x32_bf16 v[112:115], v[138:141], v[190:193], v[112:115]
	v_mfma_f32_16x16x32_bf16 v[108:111], v[146:149], v[190:193], v[108:111]
	v_mfma_f32_16x16x32_bf16 v[104:107], v[138:141], v[198:201], v[104:107]
	v_mfma_f32_16x16x32_bf16 v[100:103], v[146:149], v[198:201], v[100:103]
	s_setprio 0
	s_barrier
	s_add_i32 s26, 0, 0x1c000
	s_add_i32 s27, s28, s33
	v_add_u32_e32 v0, s26, v159
	v_lshl_add_u64 v[210:211], v[210:211], 0, s[8:9]
	s_mov_b32 m0, s27
	ds_read_b128 v[202:205], v0
	ds_read_b128 v[206:209], v0 offset:1024
	ds_read_b128 v[214:217], v0 offset:2048
	ds_read_b128 v[218:221], v0 offset:3072
	global_load_lds_dwordx4 v[210:211], off
	v_lshl_add_u64 v[210:211], v[222:223], 0, s[8:9]
	s_add_i32 m0, s27, 0x2000
	s_nop 0
	global_load_lds_dwordx4 v[210:211], off
	s_barrier
	s_waitcnt lgkmcnt(0)
	s_setprio 1
	s_waitcnt lgkmcnt(0)
	v_mfma_f32_16x16x32_bf16 v[96:99], v[202:205], v[170:173], v[96:99]
	v_mfma_f32_16x16x32_bf16 v[92:95], v[214:217], v[170:173], v[92:95]
	v_mfma_f32_16x16x32_bf16 v[88:91], v[202:205], v[178:181], v[88:91]
	v_mfma_f32_16x16x32_bf16 v[84:87], v[214:217], v[178:181], v[84:87]
	v_mfma_f32_16x16x32_bf16 v[80:83], v[202:205], v[186:189], v[80:83]
	v_mfma_f32_16x16x32_bf16 v[76:79], v[214:217], v[186:189], v[76:79]
	v_mfma_f32_16x16x32_bf16 v[72:75], v[202:205], v[194:197], v[72:75]
	v_mfma_f32_16x16x32_bf16 v[68:71], v[214:217], v[194:197], v[68:71]
	v_mfma_f32_16x16x32_bf16 v[96:99], v[206:209], v[174:177], v[96:99]
	v_mfma_f32_16x16x32_bf16 v[92:95], v[218:221], v[174:177], v[92:95]
	v_mfma_f32_16x16x32_bf16 v[88:91], v[206:209], v[182:185], v[88:91]
	v_mfma_f32_16x16x32_bf16 v[84:87], v[218:221], v[182:185], v[84:87]
	v_mfma_f32_16x16x32_bf16 v[80:83], v[206:209], v[190:193], v[80:83]
	v_mfma_f32_16x16x32_bf16 v[76:79], v[218:221], v[190:193], v[76:79]
	v_mfma_f32_16x16x32_bf16 v[72:75], v[206:209], v[198:201], v[72:75]
	v_mfma_f32_16x16x32_bf16 v[68:71], v[218:221], v[198:201], v[68:71]
	s_setprio 0
	s_mov_b32 m0, s43
	v_lshl_add_u64 v[210:211], v[228:229], 0, s[8:9]
	s_barrier
	ds_read_b128 v[170:173], v165 offset:49152
	ds_read_b128 v[174:177], v165 offset:50176
	ds_read_b128 v[178:181], v165 offset:51200
	ds_read_b128 v[182:185], v165 offset:52224
	ds_read_b128 v[186:189], v165 offset:53248
	ds_read_b128 v[190:193], v165 offset:54272
	ds_read_b128 v[194:197], v165 offset:55296
	ds_read_b128 v[198:201], v165 offset:56320
	global_load_lds_dwordx4 v[210:211], off
	v_lshl_add_u64 v[210:211], v[230:231], 0, s[8:9]
	s_mov_b32 m0, s44
	s_nop 0
	global_load_lds_dwordx4 v[210:211], off
	s_barrier
; __device__ __forceinline__ float sigmoidf_(float x) { return __builtin_amdgcn_rcpf(1.0f + __expf(-x)); }
; #define PG8_LDA(dst, b, h) do { _Pragma("unroll") for (int m = 0; m < 4; ++m) _Pragma("unroll") for (int k = 0; k < 2; ++k) dst[m][k] = *(const LAS bf16x8*)(lds + PG8_SA(b, h) + aoff + m * 2048 + k * 1024); } while (0)
; #define PG8_MMA(ai, bj, At, Bt) do { __builtin_amdgcn_s_setprio(1); _Pragma("unroll") for (int m = 0; m < 4; ++m) _Pragma("unroll") for (int n = 0; n < 2; ++n) _Pragma("unroll") for (int k = 0; k < 2; ++k) \
;         acc[ai][bj][m][n] = __builtin_amdgcn_mfma_f32_16x16x32_bf16(Bt[n][k], At[m][k], acc[ai][bj][m][n], 0, 0, 0); __builtin_amdgcn_s_setprio(0); } while (0)
; #define PG8_BAR __builtin_amdgcn_s_barrier()
; template <class EpiMid, class EpiEnd>
; __device__ __forceinline__ void gemm_phase2(LAS unsigned char* lds, const Gemm g0, const Gemm g1, const StaticOrder& S, const EpiMid& Emid, const EpiEnd& Eend) {
;     ...
;                 PG8_BAR; PG8_WAIT_L(0); PG8_MMA(0, 1, At, B1); PG8_BAR;
;                 PG8_LDA(At, 1, 1); PG8_STAGE2(PG8_SA(1, 0), a3, rA2, K2);
;                 PG8_BAR; PG8_WAIT_L(0); PG8_MMA(1, 0, At, B0); PG8_BAR; PG8_SCHED;
;                 PG8_STAGE2(PG8_SB(1, 1), b3 + h2, rB2, K2);
;                 PG8_WAIT_V(6); PG8_BAR; PG8_MMA(1, 1, At, B1); PG8_BAR;
;             }
;             if (seg == 0) Emid(acc, cur, wr, wc, fr, fq); else Eend(acc, cur, wr, wc, fr, fq);
;     __device__ __forceinline__ void operator()(f32x4 (&acc)[2][2][4][2], const pg8::Unit& u, int wr, int wc, int fr, int fq) const {
;     ...
;         for (int ai = 0; ai < 2; ++ai) {
;             u32x4 ga[4][2];
; #pragma unroll
;             for (int m = 0; m < 4; ++m)
; #pragma unroll
;                 for (int bj = 0; bj < 2; ++bj) ga[m][bj] = __builtin_nontemporal_load((const u32x4*)((const char*)Gt + (goff + (unsigned)(ai * 128 + m * 16) * 4096u + 256u * bj)));
; #pragma unroll
;             for (int m = 0; m < 4; ++m) {
;                 const unsigned rm = moff + (unsigned)(ai * 128 + m * 16) * 2048u;
; #pragma unroll
;                 for (int bj = 0; bj < 2; ++bj) {
;                     float fa[8], o[8]; unpack8(ga[m][bj], fa);
; #pragma unroll
;                     for (int e = 0; e < 8; ++e) o[e] = sigmoidf_(fa[e]) * acc[ai][bj][m][e >> 2][e & 3];
;                     *(u32x4*)((char*)MG + (rm + 256u * bj)) = pack8(o);
	s_waitcnt lgkmcnt(0)
	s_setprio 1
	s_waitcnt lgkmcnt(0)
	v_mfma_f32_16x16x32_bf16 v[64:67], v[134:137], v[170:173], v[64:67]
	v_mfma_f32_16x16x32_bf16 v[60:63], v[142:145], v[170:173], v[60:63]
	v_mfma_f32_16x16x32_bf16 v[56:59], v[134:137], v[178:181], v[56:59]
	v_mfma_f32_16x16x32_bf16 v[52:55], v[142:145], v[178:181], v[52:55]
	v_mfma_f32_16x16x32_bf16 v[48:51], v[134:137], v[186:189], v[48:51]
	v_mfma_f32_16x16x32_bf16 v[44:47], v[142:145], v[186:189], v[44:47]
	v_mfma_f32_16x16x32_bf16 v[40:43], v[134:137], v[194:197], v[40:43]
	v_mfma_f32_16x16x32_bf16 v[36:39], v[142:145], v[194:197], v[36:39]
	v_mfma_f32_16x16x32_bf16 v[64:67], v[138:141], v[174:177], v[64:67]
	v_mfma_f32_16x16x32_bf16 v[60:63], v[146:149], v[174:177], v[60:63]
	v_mfma_f32_16x16x32_bf16 v[56:59], v[138:141], v[182:185], v[56:59]
	v_mfma_f32_16x16x32_bf16 v[52:55], v[146:149], v[182:185], v[52:55]
	v_mfma_f32_16x16x32_bf16 v[48:51], v[138:141], v[190:193], v[48:51]
	v_mfma_f32_16x16x32_bf16 v[44:47], v[146:149], v[190:193], v[44:47]
	v_mfma_f32_16x16x32_bf16 v[40:43], v[138:141], v[198:201], v[40:43]
	v_mfma_f32_16x16x32_bf16 v[36:39], v[146:149], v[198:201], v[36:39]
	s_setprio 0
	s_barrier
	s_add_i32 s26, s26, s33
	v_lshl_add_u64 v[134:135], v[232:233], 0, s[8:9]
	s_mov_b32 m0, s26
	s_nop 0
	global_load_lds_dwordx4 v[134:135], off
	v_lshl_add_u64 v[134:135], v[150:151], 0, s[8:9]
	s_add_i32 m0, s26, 0x2000
	s_nop 0
	global_load_lds_dwordx4 v[134:135], off
	s_waitcnt vmcnt(6)
	global_load_dword v242, v240, s[96:97]
	v_add_u32_e32 v240, 0x10000, v240
	s_barrier
	s_setprio 1
	v_mfma_f32_16x16x32_bf16 v[32:35], v[202:205], v[170:173], v[32:35]
	v_mfma_f32_16x16x32_bf16 v[28:31], v[214:217], v[170:173], v[28:31]
	v_mfma_f32_16x16x32_bf16 v[24:27], v[202:205], v[178:181], v[24:27]
	v_mfma_f32_16x16x32_bf16 v[20:23], v[214:217], v[178:181], v[20:23]
	v_mfma_f32_16x16x32_bf16 v[16:19], v[202:205], v[186:189], v[16:19]
	v_mfma_f32_16x16x32_bf16 v[12:15], v[214:217], v[186:189], v[12:15]
	v_mfma_f32_16x16x32_bf16 v[8:11], v[202:205], v[194:197], v[8:11]
	v_mfma_f32_16x16x32_bf16 v[4:7], v[214:217], v[194:197], v[4:7]
	v_mfma_f32_16x16x32_bf16 v[32:35], v[206:209], v[174:177], v[32:35]
	v_mfma_f32_16x16x32_bf16 v[28:31], v[218:221], v[174:177], v[28:31]
	v_mfma_f32_16x16x32_bf16 v[24:27], v[206:209], v[182:185], v[24:27]
	v_mfma_f32_16x16x32_bf16 v[20:23], v[218:221], v[182:185], v[20:23]
	v_mfma_f32_16x16x32_bf16 v[16:19], v[206:209], v[190:193], v[16:19]
	v_mfma_f32_16x16x32_bf16 v[12:15], v[218:221], v[190:193], v[12:15]
	v_mfma_f32_16x16x32_bf16 v[8:11], v[206:209], v[198:201], v[8:11]
	v_mfma_f32_16x16x32_bf16 v[4:7], v[218:221], v[198:201], v[4:7]
	s_setprio 0
	s_add_u32 s24, s24, 0x100
	s_addc_u32 s25, s25, 0
	s_cmp_ge_u32 s54, s52
	s_barrier
	s_cbranch_scc0 .LBB0_772
	s_mov_b64 s[20:21], -1
	s_and_b64 vcc, exec, s[18:19]
	s_cbranch_vccz .LBB0_775
	v_mov_b32_e32 v2, v166
	v_mov_b32_e32 v0, v167
	global_load_dwordx4 v[170:173], v2, s[94:95] nt
	v_add_u32_e32 v3, 0x100, v2
	global_load_dwordx4 v[174:177], v3, s[94:95] nt
	v_add_u32_e32 v3, 0x10000, v2
	v_add_u32_e32 v132, 0x10100, v2
	v_add_u32_e32 v133, 0x20000, v2
	v_add_u32_e32 v134, 0x20100, v2
	v_add_u32_e32 v135, 0x30000, v2
	v_add_u32_e32 v169, 0x30100, v2
	global_load_dwordx4 v[178:181], v3, s[94:95] nt
	global_load_dwordx4 v[148:151], v132, s[94:95] nt
	global_load_dwordx4 v[144:147], v133, s[94:95] nt
	global_load_dwordx4 v[140:143], v134, s[94:95] nt
	global_load_dwordx4 v[136:139], v135, s[94:95] nt
	s_nop 0
	global_load_dwordx4 v[132:135], v169, s[94:95] nt
	s_mov_b64 s[20:21], 0
	s_waitcnt vmcnt(0)
	v_lshlrev_b32_e32 v3, 16, v170
	v_and_b32_e32 v169, 0xffff0000, v170
	v_lshlrev_b32_e32 v170, 16, v171
	v_and_b32_e32 v171, 0xffff0000, v171
	v_lshlrev_b32_e32 v182, 16, v172
	v_and_b32_e32 v172, 0xffff0000, v172
	v_lshlrev_b32_e32 v183, 16, v173
	v_and_b32_e32 v173, 0xffff0000, v173
	v_mul_f32_e32 v3, 0xbfb8aa3b, v3
	v_mul_f32_e32 v169, 0xbfb8aa3b, v169
	v_mul_f32_e32 v170, 0xbfb8aa3b, v170
	v_mul_f32_e32 v171, 0xbfb8aa3b, v171
	v_mul_f32_e32 v182, 0xbfb8aa3b, v182
	v_mul_f32_e32 v172, 0xbfb8aa3b, v172
	v_mul_f32_e32 v183, 0xbfb8aa3b, v183
	v_mul_f32_e32 v173, 0xbfb8aa3b, v173
	v_lshlrev_b32_e32 v187, 16, v177
	v_and_b32_e32 v188, 0xffff0000, v177
	v_exp_f32_e32 v3, v3
	v_exp_f32_e32 v169, v169
	v_exp_f32_e32 v170, v170
	v_exp_f32_e32 v171, v171
	v_exp_f32_e32 v177, v182
	v_exp_f32_e32 v172, v172
	v_exp_f32_e32 v182, v183
	v_exp_f32_e32 v173, v173
	v_lshlrev_b32_e32 v184, 16, v174
	v_and_b32_e32 v174, 0xffff0000, v174
	v_lshlrev_b32_e32 v185, 16, v175
	v_and_b32_e32 v175, 0xffff0000, v175
	v_lshlrev_b32_e32 v186, 16, v176
	v_and_b32_e32 v176, 0xffff0000, v176
	v_mul_f32_e32 v174, 0xbfb8aa3b, v174
	v_mul_f32_e32 v175, 0xbfb8aa3b, v175
	v_mul_f32_e32 v176, 0xbfb8aa3b, v176
	v_mul_f32_e32 v183, 0xbfb8aa3b, v184
	v_mul_f32_e32 v184, 0xbfb8aa3b, v185
	v_mul_f32_e32 v185, 0xbfb8aa3b, v186
	v_exp_f32_e32 v186, v174
	v_exp_f32_e32 v189, v175
	v_exp_f32_e32 v190, v176
	v_add_f32_e32 v3, 1.0, v3
	v_add_f32_e32 v169, 1.0, v169
	v_add_f32_e32 v174, 1.0, v170
	v_add_f32_e32 v175, 1.0, v171
	v_add_f32_e32 v176, 1.0, v177
	v_add_f32_e32 v177, 1.0, v172
	v_add_f32_e32 v182, 1.0, v182
	v_add_f32_e32 v191, 1.0, v173
	v_rcp_f32_e32 v170, v3
	v_rcp_f32_e32 v171, v169
	v_rcp_f32_e32 v172, v174
	v_rcp_f32_e32 v173, v175
	v_rcp_f32_e32 v174, v176
	v_rcp_f32_e32 v175, v177
	v_rcp_f32_e32 v176, v182
	v_rcp_f32_e32 v177, v191
	v_exp_f32_e32 v183, v183
	v_add_f32_e32 v169, 1.0, v186
	v_pk_mul_f32 v[170:171], v[128:129], v[170:171]
	v_pk_mul_f32 v[172:173], v[130:131], v[172:173]
	v_pk_mul_f32 v[174:175], v[124:125], v[174:175]
; __device__ __forceinline__ float sigmoidf_(float x) { return __builtin_amdgcn_rcpf(1.0f + __expf(-x)); }
;     __device__ __forceinline__ void operator()(f32x4 (&acc)[2][2][4][2], const pg8::Unit& u, int wr, int wc, int fr, int fq) const {
;     ...
;             for (int m = 0; m < 4; ++m)
; #pragma unroll
;                 for (int bj = 0; bj < 2; ++bj) ga[m][bj] = __builtin_nontemporal_load((const u32x4*)((const char*)Gt + (goff + (unsigned)(ai * 128 + m * 16) * 4096u + 256u * bj)));
; #pragma unroll
;             for (int m = 0; m < 4; ++m) {
;                 const unsigned rm = moff + (unsigned)(ai * 128 + m * 16) * 2048u;
; #pragma unroll
;                 for (int bj = 0; bj < 2; ++bj) {
;                     float fa[8], o[8]; unpack8(ga[m][bj], fa);
; #pragma unroll
;                     for (int e = 0; e < 8; ++e) o[e] = sigmoidf_(fa[e]) * acc[ai][bj][m][e >> 2][e & 3];
;                     *(u32x4*)((char*)MG + (rm + 256u * bj)) = pack8(o);
;                 }
	v_pk_mul_f32 v[176:177], v[126:127], v[176:177]
	v_add_f32_e32 v3, 1.0, v183
	v_rcp_f32_e32 v183, v169
	v_cvt_pk_bf16_f32 v170, v170, v171
	v_cvt_pk_bf16_f32 v171, v172, v173
	v_cvt_pk_bf16_f32 v172, v174, v175
	v_cvt_pk_bf16_f32 v173, v176, v177
	v_mul_f32_e32 v169, 0xbfb8aa3b, v187
	global_store_dwordx4 v0, v[170:173], s[4:5]
	v_exp_f32_e32 v169, v169
	v_exp_f32_e32 v184, v184
	v_mul_f32_e32 v171, 0xbfb8aa3b, v188
	v_exp_f32_e32 v185, v185
	v_exp_f32_e32 v173, v171
	v_rcp_f32_e32 v182, v3
	v_add_f32_e32 v3, 1.0, v190
	v_rcp_f32_e32 v171, v3
	v_add_f32_e32 v3, 1.0, v169
	v_add_f32_e32 v184, 1.0, v184
	v_add_f32_e32 v186, 1.0, v189
	v_add_f32_e32 v189, 1.0, v185
	v_rcp_f32_e32 v172, v3
	v_add_f32_e32 v3, 1.0, v173
	v_rcp_f32_e32 v184, v184
	v_rcp_f32_e32 v185, v186
	v_rcp_f32_e32 v170, v189
	v_rcp_f32_e32 v173, v3
	v_pk_mul_f32 v[174:175], v[96:97], v[182:183]
	v_pk_mul_f32 v[176:177], v[98:99], v[184:185]
	v_pk_mul_f32 v[182:183], v[92:93], v[170:171]
	v_pk_mul_f32 v[184:185], v[94:95], v[172:173]
	v_cvt_pk_bf16_f32 v170, v174, v175
	v_cvt_pk_bf16_f32 v171, v176, v177
	v_cvt_pk_bf16_f32 v172, v182, v183
	v_cvt_pk_bf16_f32 v173, v184, v185
	v_add_u32_e32 v3, 0x100, v0
	v_lshlrev_b32_e32 v169, 16, v178
	global_store_dwordx4 v3, v[170:173], s[4:5]
	v_mul_f32_e32 v169, 0xbfb8aa3b, v169
	v_exp_f32_e32 v169, v169
	v_and_b32_e32 v170, 0xffff0000, v178
	v_mul_f32_e32 v170, 0xbfb8aa3b, v170
	v_exp_f32_e32 v176, v170
	v_lshlrev_b32_e32 v171, 16, v179
	v_add_f32_e32 v169, 1.0, v169
	v_mul_f32_e32 v171, 0xbfb8aa3b, v171
	v_rcp_f32_e32 v170, v169
	v_add_f32_e32 v169, 1.0, v176
	v_exp_f32_e32 v176, v171
	v_and_b32_e32 v172, 0xffff0000, v179
	v_lshlrev_b32_e32 v173, 16, v180
	v_mul_f32_e32 v171, 0xbfb8aa3b, v172
	v_exp_f32_e32 v178, v171
	v_mul_f32_e32 v173, 0xbfb8aa3b, v173
	v_rcp_f32_e32 v171, v169
	v_add_f32_e32 v169, 1.0, v176
	v_exp_f32_e32 v176, v173
	v_and_b32_e32 v174, 0xffff0000, v180
	v_lshlrev_b32_e32 v175, 16, v181
	v_mul_f32_e32 v173, 0xbfb8aa3b, v174
	v_and_b32_e32 v177, 0xffff0000, v181
	v_rcp_f32_e32 v172, v169
	v_add_f32_e32 v169, 1.0, v178
	v_exp_f32_e32 v178, v173
	v_mul_f32_e32 v175, 0xbfb8aa3b, v175
	v_rcp_f32_e32 v173, v169
	v_add_f32_e32 v169, 1.0, v176
	v_exp_f32_e32 v176, v175
	v_mul_f32_e32 v175, 0xbfb8aa3b, v177
	v_exp_f32_e32 v177, v175
	v_rcp_f32_e32 v174, v169
	v_add_f32_e32 v169, 1.0, v178
	v_rcp_f32_e32 v175, v169
	v_add_f32_e32 v169, 1.0, v176
	v_rcp_f32_e32 v176, v169
	v_add_f32_e32 v169, 1.0, v177
	v_rcp_f32_e32 v177, v169
	v_pk_mul_f32 v[170:171], v[120:121], v[170:171]
	v_pk_mul_f32 v[172:173], v[122:123], v[172:173]
	v_pk_mul_f32 v[174:175], v[116:117], v[174:175]
	v_pk_mul_f32 v[176:177], v[118:119], v[176:177]
	v_add_u32_e32 v3, 0x8000, v0
	v_cvt_pk_bf16_f32 v170, v170, v171
	v_cvt_pk_bf16_f32 v171, v172, v173
	v_cvt_pk_bf16_f32 v172, v174, v175
	v_cvt_pk_bf16_f32 v173, v176, v177
	global_store_dwordx4 v3, v[170:173], s[4:5]
	v_lshlrev_b32_e32 v3, 16, v148
	v_and_b32_e32 v148, 0xffff0000, v148
	v_mul_f32_e32 v3, 0xbfb8aa3b, v3
	v_exp_f32_e32 v3, v3
	v_mul_f32_e32 v148, 0xbfb8aa3b, v148
	v_lshlrev_b32_e32 v170, 16, v150
	v_and_b32_e32 v171, 0xffff0000, v150
	v_exp_f32_e32 v150, v148
	v_lshlrev_b32_e32 v169, 16, v149
	v_add_f32_e32 v3, 1.0, v3
	v_and_b32_e32 v149, 0xffff0000, v149
	v_rcp_f32_e32 v148, v3
	v_add_f32_e32 v3, 1.0, v150
	v_mul_f32_e32 v150, 0xbfb8aa3b, v169
	v_exp_f32_e32 v150, v150
	v_mul_f32_e32 v149, 0xbfb8aa3b, v149
	v_lshlrev_b32_e32 v172, 16, v151
	v_and_b32_e32 v173, 0xffff0000, v151
	v_exp_f32_e32 v151, v149
	v_rcp_f32_e32 v149, v3
	v_add_f32_e32 v3, 1.0, v150
	v_rcp_f32_e32 v150, v3
	v_add_f32_e32 v3, 1.0, v151
	v_mul_f32_e32 v151, 0xbfb8aa3b, v170
	v_exp_f32_e32 v169, v151
	v_mul_f32_e32 v151, 0xbfb8aa3b, v171
	v_exp_f32_e32 v171, v151
	v_rcp_f32_e32 v151, v3
	v_add_f32_e32 v3, 1.0, v169
	v_mul_f32_e32 v169, 0xbfb8aa3b, v172
	v_rcp_f32_e32 v170, v3
	v_add_f32_e32 v3, 1.0, v171
	v_exp_f32_e32 v169, v169
	v_mul_f32_e32 v171, 0xbfb8aa3b, v173
	v_exp_f32_e32 v173, v171
	v_rcp_f32_e32 v171, v3
	v_add_f32_e32 v3, 1.0, v169
	v_rcp_f32_e32 v172, v3
	v_add_f32_e32 v3, 1.0, v173
	v_rcp_f32_e32 v173, v3
	v_pk_mul_f32 v[148:149], v[88:89], v[148:149]
	v_pk_mul_f32 v[150:151], v[90:91], v[150:151]
	v_pk_mul_f32 v[170:171], v[84:85], v[170:171]
	v_pk_mul_f32 v[172:173], v[86:87], v[172:173]
	v_cvt_pk_bf16_f32 v148, v148, v149
	v_cvt_pk_bf16_f32 v149, v150, v151
	v_cvt_pk_bf16_f32 v150, v170, v171
	v_cvt_pk_bf16_f32 v151, v172, v173
	v_add_u32_e32 v3, 0x8100, v0
	global_store_dwordx4 v3, v[148:151], s[4:5]
	v_lshlrev_b32_e32 v169, 16, v147
	v_and_b32_e32 v170, 0xffff0000, v147
	v_lshlrev_b32_e32 v148, 16, v144
	v_and_b32_e32 v144, 0xffff0000, v144
	v_lshlrev_b32_e32 v150, 16, v146
	v_and_b32_e32 v151, 0xffff0000, v146
	v_mul_f32_e32 v146, 0xbfb8aa3b, v148
	v_mul_f32_e32 v144, 0xbfb8aa3b, v144
	v_exp_f32_e32 v146, v146
	v_exp_f32_e32 v148, v144
	v_lshlrev_b32_e32 v149, 16, v145
	v_and_b32_e32 v145, 0xffff0000, v145
	v_mul_f32_e32 v147, 0xbfb8aa3b, v149
	v_mul_f32_e32 v145, 0xbfb8aa3b, v145
	v_add_f32_e32 v144, 1.0, v146
	v_add_f32_e32 v146, 1.0, v148
	v_exp_f32_e32 v147, v147
	v_exp_f32_e32 v148, v145
	v_rcp_f32_e32 v145, v146
	v_mul_f32_e32 v149, 0xbfb8aa3b, v151
	v_add_f32_e32 v146, 1.0, v147
	v_add_f32_e32 v147, 1.0, v148
	v_mul_f32_e32 v148, 0xbfb8aa3b, v150
	v_mul_f32_e32 v150, 0xbfb8aa3b, v169
	v_mul_f32_e32 v151, 0xbfb8aa3b, v170
	v_exp_f32_e32 v148, v148
	v_exp_f32_e32 v149, v149
	v_exp_f32_e32 v150, v150
	v_exp_f32_e32 v151, v151
	v_add_f32_e32 v148, 1.0, v148
	v_add_f32_e32 v149, 1.0, v149
	v_add_f32_e32 v150, 1.0, v150
	v_add_f32_e32 v151, 1.0, v151
	v_rcp_f32_e32 v144, v144
	v_rcp_f32_e32 v146, v146
; __device__ __forceinline__ float sigmoidf_(float x) { return __builtin_amdgcn_rcpf(1.0f + __expf(-x)); }
;     __device__ __forceinline__ void operator()(f32x4 (&acc)[2][2][4][2], const pg8::Unit& u, int wr, int wc, int fr, int fq) const {
;     ...
;             for (int m = 0; m < 4; ++m)
; #pragma unroll
;                 for (int bj = 0; bj < 2; ++bj) ga[m][bj] = __builtin_nontemporal_load((const u32x4*)((const char*)Gt + (goff + (unsigned)(ai * 128 + m * 16) * 4096u + 256u * bj)));
; #pragma unroll
;             for (int m = 0; m < 4; ++m) {
;                 const unsigned rm = moff + (unsigned)(ai * 128 + m * 16) * 2048u;
; #pragma unroll
;                 for (int bj = 0; bj < 2; ++bj) {
;                     float fa[8], o[8]; unpack8(ga[m][bj], fa);
; #pragma unroll
;                     for (int e = 0; e < 8; ++e) o[e] = sigmoidf_(fa[e]) * acc[ai][bj][m][e >> 2][e & 3];
;                     *(u32x4*)((char*)MG + (rm + 256u * bj)) = pack8(o);
;                 }
	v_rcp_f32_e32 v147, v147
	v_rcp_f32_e32 v148, v148
	v_rcp_f32_e32 v149, v149
	v_rcp_f32_e32 v150, v150
	v_rcp_f32_e32 v151, v151
	v_pk_mul_f32 v[144:145], v[112:113], v[144:145]
	v_pk_mul_f32 v[146:147], v[114:115], v[146:147]
	v_pk_mul_f32 v[148:149], v[108:109], v[148:149]
	v_pk_mul_f32 v[150:151], v[110:111], v[150:151]
	v_add_u32_e32 v3, 0x10000, v0
	v_cvt_pk_bf16_f32 v144, v144, v145
	v_cvt_pk_bf16_f32 v145, v146, v147
	v_cvt_pk_bf16_f32 v146, v148, v149
	v_cvt_pk_bf16_f32 v147, v150, v151
	global_store_dwordx4 v3, v[144:147], s[4:5]
	v_lshlrev_b32_e32 v3, 16, v140
	v_and_b32_e32 v140, 0xffff0000, v140
	v_mul_f32_e32 v3, 0xbfb8aa3b, v3
	v_exp_f32_e32 v3, v3
	v_mul_f32_e32 v140, 0xbfb8aa3b, v140
	v_lshlrev_b32_e32 v145, 16, v142
	v_and_b32_e32 v146, 0xffff0000, v142
	v_exp_f32_e32 v142, v140
	v_lshlrev_b32_e32 v144, 16, v141
	v_add_f32_e32 v3, 1.0, v3
	v_and_b32_e32 v141, 0xffff0000, v141
	v_rcp_f32_e32 v140, v3
	v_add_f32_e32 v3, 1.0, v142
	v_mul_f32_e32 v142, 0xbfb8aa3b, v144
	v_exp_f32_e32 v142, v142
	v_mul_f32_e32 v141, 0xbfb8aa3b, v141
	v_lshlrev_b32_e32 v147, 16, v143
	v_and_b32_e32 v148, 0xffff0000, v143
	v_exp_f32_e32 v143, v141
	v_rcp_f32_e32 v141, v3
	v_add_f32_e32 v3, 1.0, v142
	v_rcp_f32_e32 v142, v3
	v_add_f32_e32 v3, 1.0, v143
	v_mul_f32_e32 v143, 0xbfb8aa3b, v145
	v_exp_f32_e32 v144, v143
	v_mul_f32_e32 v143, 0xbfb8aa3b, v146
	v_exp_f32_e32 v145, v143
	v_rcp_f32_e32 v143, v3
	v_add_f32_e32 v3, 1.0, v144
	v_rcp_f32_e32 v144, v3
	v_add_f32_e32 v3, 1.0, v145
	v_mul_f32_e32 v145, 0xbfb8aa3b, v147
	v_exp_f32_e32 v146, v145
	v_mul_f32_e32 v145, 0xbfb8aa3b, v148
	v_exp_f32_e32 v147, v145
	v_rcp_f32_e32 v145, v3
	v_add_f32_e32 v3, 1.0, v146
	v_rcp_f32_e32 v146, v3
	v_add_f32_e32 v3, 1.0, v147
	v_rcp_f32_e32 v147, v3
	v_pk_mul_f32 v[140:141], v[80:81], v[140:141]
	v_pk_mul_f32 v[142:143], v[82:83], v[142:143]
	v_pk_mul_f32 v[144:145], v[76:77], v[144:145]
	v_pk_mul_f32 v[146:147], v[78:79], v[146:147]
	v_cvt_pk_bf16_f32 v140, v140, v141
	v_cvt_pk_bf16_f32 v141, v142, v143
	v_cvt_pk_bf16_f32 v142, v144, v145
	v_cvt_pk_bf16_f32 v143, v146, v147
	v_add_u32_e32 v3, 0x10100, v0
	global_store_dwordx4 v3, v[140:143], s[4:5]
	v_lshlrev_b32_e32 v144, 16, v139
	v_and_b32_e32 v145, 0xffff0000, v139
	v_lshlrev_b32_e32 v140, 16, v136
	v_and_b32_e32 v136, 0xffff0000, v136
	v_lshlrev_b32_e32 v142, 16, v138
	v_and_b32_e32 v143, 0xffff0000, v138
	v_mul_f32_e32 v138, 0xbfb8aa3b, v140
	v_mul_f32_e32 v136, 0xbfb8aa3b, v136
	v_exp_f32_e32 v138, v138
	v_exp_f32_e32 v140, v136
	v_lshlrev_b32_e32 v141, 16, v137
	v_and_b32_e32 v137, 0xffff0000, v137
	v_mul_f32_e32 v139, 0xbfb8aa3b, v141
	v_mul_f32_e32 v137, 0xbfb8aa3b, v137
	v_add_f32_e32 v136, 1.0, v138
	v_add_f32_e32 v138, 1.0, v140
	v_exp_f32_e32 v139, v139
	v_exp_f32_e32 v140, v137
	v_rcp_f32_e32 v137, v138
	v_mul_f32_e32 v141, 0xbfb8aa3b, v143
	v_add_f32_e32 v138, 1.0, v139
	v_add_f32_e32 v139, 1.0, v140
	v_mul_f32_e32 v140, 0xbfb8aa3b, v142
	v_mul_f32_e32 v142, 0xbfb8aa3b, v144
	v_mul_f32_e32 v143, 0xbfb8aa3b, v145
	v_exp_f32_e32 v140, v140
	v_exp_f32_e32 v141, v141
	v_exp_f32_e32 v142, v142
	v_exp_f32_e32 v143, v143
	v_add_f32_e32 v140, 1.0, v140
	v_add_f32_e32 v141, 1.0, v141
	v_add_f32_e32 v142, 1.0, v142
	v_add_f32_e32 v143, 1.0, v143
	v_rcp_f32_e32 v136, v136
	v_rcp_f32_e32 v138, v138
	v_rcp_f32_e32 v139, v139
	v_rcp_f32_e32 v140, v140
	v_rcp_f32_e32 v141, v141
	v_rcp_f32_e32 v142, v142
	v_rcp_f32_e32 v143, v143
	v_pk_mul_f32 v[136:137], v[104:105], v[136:137]
	v_pk_mul_f32 v[138:139], v[106:107], v[138:139]
	v_pk_mul_f32 v[140:141], v[100:101], v[140:141]
	v_pk_mul_f32 v[142:143], v[102:103], v[142:143]
	v_add_u32_e32 v3, 0x18000, v0
	v_cvt_pk_bf16_f32 v136, v136, v137
	v_cvt_pk_bf16_f32 v137, v138, v139
	v_cvt_pk_bf16_f32 v138, v140, v141
	v_cvt_pk_bf16_f32 v139, v142, v143
	global_store_dwordx4 v3, v[136:139], s[4:5]
	v_lshlrev_b32_e32 v3, 16, v132
	v_and_b32_e32 v132, 0xffff0000, v132
	v_mul_f32_e32 v3, 0xbfb8aa3b, v3
	v_exp_f32_e32 v3, v3
	v_mul_f32_e32 v132, 0xbfb8aa3b, v132
	v_lshlrev_b32_e32 v137, 16, v134
	v_and_b32_e32 v138, 0xffff0000, v134
	v_exp_f32_e32 v134, v132
	v_lshlrev_b32_e32 v136, 16, v133
	v_add_f32_e32 v3, 1.0, v3
	v_and_b32_e32 v133, 0xffff0000, v133
	v_rcp_f32_e32 v132, v3
	v_add_f32_e32 v3, 1.0, v134
	v_mul_f32_e32 v134, 0xbfb8aa3b, v136
	v_exp_f32_e32 v134, v134
	v_mul_f32_e32 v133, 0xbfb8aa3b, v133
	v_lshlrev_b32_e32 v139, 16, v135
	v_and_b32_e32 v140, 0xffff0000, v135
	v_exp_f32_e32 v135, v133
	v_rcp_f32_e32 v133, v3
	v_add_f32_e32 v3, 1.0, v134
	v_rcp_f32_e32 v134, v3
	v_add_f32_e32 v3, 1.0, v135
	v_mul_f32_e32 v135, 0xbfb8aa3b, v137
	v_exp_f32_e32 v136, v135
	v_mul_f32_e32 v135, 0xbfb8aa3b, v138
	v_exp_f32_e32 v137, v135
	v_rcp_f32_e32 v135, v3
	v_add_f32_e32 v3, 1.0, v136
	v_rcp_f32_e32 v136, v3
	v_add_f32_e32 v3, 1.0, v137
	v_mul_f32_e32 v137, 0xbfb8aa3b, v139
	v_exp_f32_e32 v138, v137
	v_mul_f32_e32 v137, 0xbfb8aa3b, v140
	v_exp_f32_e32 v139, v137
	v_rcp_f32_e32 v137, v3
	v_add_f32_e32 v3, 1.0, v138
	v_rcp_f32_e32 v138, v3
	v_add_f32_e32 v3, 1.0, v139
	v_rcp_f32_e32 v139, v3
	v_pk_mul_f32 v[132:133], v[72:73], v[132:133]
	v_pk_mul_f32 v[134:135], v[74:75], v[134:135]
	v_pk_mul_f32 v[136:137], v[68:69], v[136:137]
	v_pk_mul_f32 v[138:139], v[70:71], v[138:139]
	v_cvt_pk_bf16_f32 v132, v132, v133
	v_cvt_pk_bf16_f32 v133, v134, v135
	v_cvt_pk_bf16_f32 v134, v136, v137
	v_cvt_pk_bf16_f32 v135, v138, v139
	v_add_u32_e32 v3, 0x18100, v0
	global_store_dwordx4 v3, v[132:135], s[4:5]
	v_add_u32_e32 v3, 0x80000, v2
	global_load_dwordx4 v[170:173], v3, s[94:95] nt
	v_add_u32_e32 v3, 0x80100, v2
	global_load_dwordx4 v[174:177], v3, s[94:95] nt
	v_add_u32_e32 v3, 0x90000, v2
	v_add_u32_e32 v132, 0x90100, v2
	global_load_dwordx4 v[178:181], v3, s[94:95] nt
	global_load_dwordx4 v[148:151], v132, s[94:95] nt
	v_add_u32_e32 v3, 0xa0000, v2
	v_add_u32_e32 v132, 0xa0100, v2
	global_load_dwordx4 v[144:147], v3, s[94:95] nt
	global_load_dwordx4 v[140:143], v132, s[94:95] nt
	v_add_u32_e32 v3, 0xb0000, v2
	v_add_u32_e32 v2, 0xb0100, v2
	global_load_dwordx4 v[136:139], v3, s[94:95] nt
	global_load_dwordx4 v[132:135], v2, s[94:95] nt
	v_add_u32_e32 v169, 0x40000, v0
	s_waitcnt vmcnt(0)
; __device__ __forceinline__ float sigmoidf_(float x) { return __builtin_amdgcn_rcpf(1.0f + __expf(-x)); }
;     __device__ __forceinline__ void operator()(f32x4 (&acc)[2][2][4][2], const pg8::Unit& u, int wr, int wc, int fr, int fq) const {
;     ...
;             for (int m = 0; m < 4; ++m)
; #pragma unroll
;                 for (int bj = 0; bj < 2; ++bj) ga[m][bj] = __builtin_nontemporal_load((const u32x4*)((const char*)Gt + (goff + (unsigned)(ai * 128 + m * 16) * 4096u + 256u * bj)));
; #pragma unroll
;             for (int m = 0; m < 4; ++m) {
;                 const unsigned rm = moff + (unsigned)(ai * 128 + m * 16) * 2048u;
; #pragma unroll
;                 for (int bj = 0; bj < 2; ++bj) {
;                     float fa[8], o[8]; unpack8(ga[m][bj], fa);
; #pragma unroll
;                     for (int e = 0; e < 8; ++e) o[e] = sigmoidf_(fa[e]) * acc[ai][bj][m][e >> 2][e & 3];
;                     *(u32x4*)((char*)MG + (rm + 256u * bj)) = pack8(o);
;                 }
	v_lshlrev_b32_e32 v182, 16, v172
	v_and_b32_e32 v172, 0xffff0000, v172
	v_mul_f32_e32 v182, 0xbfb8aa3b, v182
	v_mul_f32_e32 v172, 0xbfb8aa3b, v172
	v_exp_f32_e32 v182, v182
	v_exp_f32_e32 v184, v172
	v_lshlrev_b32_e32 v2, 16, v170
	v_and_b32_e32 v3, 0xffff0000, v170
	v_lshlrev_b32_e32 v170, 16, v171
	v_and_b32_e32 v171, 0xffff0000, v171
	v_lshlrev_b32_e32 v183, 16, v173
	v_and_b32_e32 v173, 0xffff0000, v173
	v_mul_f32_e32 v2, 0xbfb8aa3b, v2
	v_mul_f32_e32 v3, 0xbfb8aa3b, v3
	v_mul_f32_e32 v170, 0xbfb8aa3b, v170
	v_mul_f32_e32 v171, 0xbfb8aa3b, v171
	v_mul_f32_e32 v183, 0xbfb8aa3b, v183
	v_mul_f32_e32 v173, 0xbfb8aa3b, v173
	v_exp_f32_e32 v2, v2
	v_exp_f32_e32 v3, v3
	v_exp_f32_e32 v170, v170
	v_exp_f32_e32 v171, v171
	v_add_f32_e32 v172, 1.0, v182
	v_add_f32_e32 v182, 1.0, v184
	v_exp_f32_e32 v183, v183
	v_exp_f32_e32 v184, v173
	v_add_f32_e32 v2, 1.0, v2
	v_add_f32_e32 v3, 1.0, v3
	v_add_f32_e32 v170, 1.0, v170
	v_add_f32_e32 v171, 1.0, v171
	v_rcp_f32_e32 v173, v182
	v_add_f32_e32 v182, 1.0, v183
	v_add_f32_e32 v183, 1.0, v184
	v_rcp_f32_e32 v2, v2
	v_rcp_f32_e32 v3, v3
	v_rcp_f32_e32 v170, v170
	v_rcp_f32_e32 v171, v171
	v_rcp_f32_e32 v172, v172
	v_rcp_f32_e32 v182, v182
	v_rcp_f32_e32 v183, v183
	v_pk_mul_f32 v[2:3], v[64:65], v[2:3]
	v_pk_mul_f32 v[184:185], v[66:67], v[170:171]
	v_pk_mul_f32 v[172:173], v[60:61], v[172:173]
	v_pk_mul_f32 v[182:183], v[62:63], v[182:183]
	v_cvt_pk_bf16_f32 v170, v2, v3
	v_cvt_pk_bf16_f32 v171, v184, v185
	v_cvt_pk_bf16_f32 v172, v172, v173
	v_cvt_pk_bf16_f32 v173, v182, v183
	global_store_dwordx4 v169, v[170:173], s[4:5]
	v_lshlrev_b32_e32 v169, 16, v175
	v_mul_f32_e32 v169, 0xbfb8aa3b, v169
	v_and_b32_e32 v170, 0xffff0000, v175
	v_exp_f32_e32 v169, v169
	v_mul_f32_e32 v170, 0xbfb8aa3b, v170
	v_exp_f32_e32 v175, v170
	v_lshlrev_b32_e32 v171, 16, v176
	v_and_b32_e32 v172, 0xffff0000, v176
	v_add_f32_e32 v169, 1.0, v169
	v_mul_f32_e32 v171, 0xbfb8aa3b, v171
	v_rcp_f32_e32 v170, v169
	v_add_f32_e32 v169, 1.0, v175
	v_exp_f32_e32 v175, v171
	v_mul_f32_e32 v171, 0xbfb8aa3b, v172
	v_exp_f32_e32 v176, v171
	v_lshlrev_b32_e32 v173, 16, v177
	v_lshlrev_b32_e32 v2, 16, v174
	v_and_b32_e32 v3, 0xffff0000, v174
	v_and_b32_e32 v174, 0xffff0000, v177
	v_mul_f32_e32 v173, 0xbfb8aa3b, v173
	v_mul_f32_e32 v2, 0xbfb8aa3b, v2
	v_mul_f32_e32 v3, 0xbfb8aa3b, v3
	v_rcp_f32_e32 v171, v169
	v_add_f32_e32 v169, 1.0, v175
	v_exp_f32_e32 v175, v173
	v_mul_f32_e32 v173, 0xbfb8aa3b, v174
	v_exp_f32_e32 v2, v2
	v_exp_f32_e32 v3, v3
	v_rcp_f32_e32 v172, v169
	v_add_f32_e32 v169, 1.0, v176
	v_exp_f32_e32 v176, v173
	v_rcp_f32_e32 v173, v169
	v_add_f32_e32 v169, 1.0, v175
	v_add_f32_e32 v2, 1.0, v2
	v_add_f32_e32 v3, 1.0, v3
	v_rcp_f32_e32 v174, v169
	v_add_f32_e32 v169, 1.0, v176
	v_rcp_f32_e32 v2, v2
	v_rcp_f32_e32 v3, v3
	v_rcp_f32_e32 v175, v169
	v_pk_mul_f32 v[176:177], v[34:35], v[170:171]
	v_pk_mul_f32 v[172:173], v[28:29], v[172:173]
	v_pk_mul_f32 v[2:3], v[32:33], v[2:3]
	v_pk_mul_f32 v[174:175], v[30:31], v[174:175]
	v_cvt_pk_bf16_f32 v170, v2, v3
	v_cvt_pk_bf16_f32 v171, v176, v177
	v_cvt_pk_bf16_f32 v172, v172, v173
	v_cvt_pk_bf16_f32 v173, v174, v175
	v_add_u32_e32 v2, 0x40100, v0
	global_store_dwordx4 v2, v[170:173], s[4:5]
	v_lshlrev_b32_e32 v2, 16, v178
	v_and_b32_e32 v3, 0xffff0000, v178
	v_lshlrev_b32_e32 v170, 16, v179
	v_and_b32_e32 v171, 0xffff0000, v179
	v_lshlrev_b32_e32 v172, 16, v180
	v_and_b32_e32 v173, 0xffff0000, v180
	v_lshlrev_b32_e32 v174, 16, v181
	v_and_b32_e32 v175, 0xffff0000, v181
	v_mul_f32_e32 v2, 0xbfb8aa3b, v2
	v_mul_f32_e32 v3, 0xbfb8aa3b, v3
	v_mul_f32_e32 v170, 0xbfb8aa3b, v170
	v_mul_f32_e32 v171, 0xbfb8aa3b, v171
	v_mul_f32_e32 v172, 0xbfb8aa3b, v172
	v_mul_f32_e32 v173, 0xbfb8aa3b, v173
	v_mul_f32_e32 v174, 0xbfb8aa3b, v174
	v_mul_f32_e32 v175, 0xbfb8aa3b, v175
	v_exp_f32_e32 v2, v2
	v_exp_f32_e32 v3, v3
	v_exp_f32_e32 v170, v170
	v_exp_f32_e32 v171, v171
	v_exp_f32_e32 v172, v172
	v_exp_f32_e32 v173, v173
	v_exp_f32_e32 v174, v174
	v_exp_f32_e32 v175, v175
	v_add_f32_e32 v2, 1.0, v2
	v_add_f32_e32 v3, 1.0, v3
	v_add_f32_e32 v170, 1.0, v170
	v_add_f32_e32 v171, 1.0, v171
	v_add_f32_e32 v172, 1.0, v172
	v_add_f32_e32 v173, 1.0, v173
	v_add_f32_e32 v174, 1.0, v174
	v_add_f32_e32 v175, 1.0, v175
	v_rcp_f32_e32 v2, v2
	v_rcp_f32_e32 v3, v3
	v_rcp_f32_e32 v170, v170
	v_rcp_f32_e32 v171, v171
	v_rcp_f32_e32 v172, v172
	v_rcp_f32_e32 v173, v173
	v_rcp_f32_e32 v174, v174
	v_rcp_f32_e32 v175, v175
	v_pk_mul_f32 v[2:3], v[56:57], v[2:3]
	v_pk_mul_f32 v[176:177], v[58:59], v[170:171]
	v_pk_mul_f32 v[172:173], v[52:53], v[172:173]
	v_pk_mul_f32 v[174:175], v[54:55], v[174:175]
	v_add_u32_e32 v169, 0x48000, v0
	v_cvt_pk_bf16_f32 v170, v2, v3
	v_cvt_pk_bf16_f32 v171, v176, v177
	v_cvt_pk_bf16_f32 v172, v172, v173
	v_cvt_pk_bf16_f32 v173, v174, v175
	global_store_dwordx4 v169, v[170:173], s[4:5]
	v_lshlrev_b32_e32 v169, 16, v150
	v_and_b32_e32 v150, 0xffff0000, v150
	v_mul_f32_e32 v169, 0xbfb8aa3b, v169
	v_mul_f32_e32 v150, 0xbfb8aa3b, v150
	v_exp_f32_e32 v169, v169
	v_exp_f32_e32 v171, v150
	v_lshlrev_b32_e32 v170, 16, v151
	v_lshlrev_b32_e32 v2, 16, v148
	v_and_b32_e32 v3, 0xffff0000, v148
	v_lshlrev_b32_e32 v148, 16, v149
	v_and_b32_e32 v149, 0xffff0000, v149
	v_and_b32_e32 v151, 0xffff0000, v151
	v_mul_f32_e32 v170, 0xbfb8aa3b, v170
	v_mul_f32_e32 v2, 0xbfb8aa3b, v2
	v_mul_f32_e32 v3, 0xbfb8aa3b, v3
	v_mul_f32_e32 v148, 0xbfb8aa3b, v148
	v_mul_f32_e32 v149, 0xbfb8aa3b, v149
	v_exp_f32_e32 v170, v170
	v_mul_f32_e32 v151, 0xbfb8aa3b, v151
	v_exp_f32_e32 v2, v2
	v_exp_f32_e32 v3, v3
	v_exp_f32_e32 v148, v148
	v_exp_f32_e32 v149, v149
	v_add_f32_e32 v150, 1.0, v169
	v_add_f32_e32 v169, 1.0, v171
; __device__ __forceinline__ float sigmoidf_(float x) { return __builtin_amdgcn_rcpf(1.0f + __expf(-x)); }
;     __device__ __forceinline__ void operator()(f32x4 (&acc)[2][2][4][2], const pg8::Unit& u, int wr, int wc, int fr, int fq) const {
;     ...
;             for (int m = 0; m < 4; ++m)
; #pragma unroll
;                 for (int bj = 0; bj < 2; ++bj) ga[m][bj] = __builtin_nontemporal_load((const u32x4*)((const char*)Gt + (goff + (unsigned)(ai * 128 + m * 16) * 4096u + 256u * bj)));
; #pragma unroll
;             for (int m = 0; m < 4; ++m) {
;                 const unsigned rm = moff + (unsigned)(ai * 128 + m * 16) * 2048u;
; #pragma unroll
;                 for (int bj = 0; bj < 2; ++bj) {
;                     float fa[8], o[8]; unpack8(ga[m][bj], fa);
; #pragma unroll
;                     for (int e = 0; e < 8; ++e) o[e] = sigmoidf_(fa[e]) * acc[ai][bj][m][e >> 2][e & 3];
;                     *(u32x4*)((char*)MG + (rm + 256u * bj)) = pack8(o);
;                 }
	v_exp_f32_e32 v171, v151
	v_rcp_f32_e32 v151, v169
	v_add_f32_e32 v169, 1.0, v170
	v_add_f32_e32 v2, 1.0, v2
	v_add_f32_e32 v3, 1.0, v3
	v_add_f32_e32 v148, 1.0, v148
	v_add_f32_e32 v149, 1.0, v149
	v_rcp_f32_e32 v170, v169
	v_add_f32_e32 v169, 1.0, v171
	v_rcp_f32_e32 v2, v2
	v_rcp_f32_e32 v3, v3
	v_rcp_f32_e32 v148, v148
	v_rcp_f32_e32 v149, v149
	v_rcp_f32_e32 v150, v150
	v_rcp_f32_e32 v171, v169
	v_pk_mul_f32 v[2:3], v[24:25], v[2:3]
	v_pk_mul_f32 v[172:173], v[26:27], v[148:149]
	v_pk_mul_f32 v[150:151], v[20:21], v[150:151]
	v_pk_mul_f32 v[170:171], v[22:23], v[170:171]
	v_cvt_pk_bf16_f32 v148, v2, v3
	v_cvt_pk_bf16_f32 v149, v172, v173
	v_cvt_pk_bf16_f32 v150, v150, v151
	v_cvt_pk_bf16_f32 v151, v170, v171
	v_add_u32_e32 v2, 0x48100, v0
	global_store_dwordx4 v2, v[148:151], s[4:5]
	v_lshlrev_b32_e32 v2, 16, v144
	v_and_b32_e32 v3, 0xffff0000, v144
	v_lshlrev_b32_e32 v148, 16, v146
	v_and_b32_e32 v146, 0xffff0000, v146
	v_mul_f32_e32 v148, 0xbfb8aa3b, v148
	v_mul_f32_e32 v146, 0xbfb8aa3b, v146
	v_exp_f32_e32 v148, v148
	v_exp_f32_e32 v150, v146
	v_lshlrev_b32_e32 v144, 16, v145
	v_and_b32_e32 v145, 0xffff0000, v145
	v_lshlrev_b32_e32 v149, 16, v147
	v_and_b32_e32 v147, 0xffff0000, v147
	v_mul_f32_e32 v2, 0xbfb8aa3b, v2
	v_mul_f32_e32 v3, 0xbfb8aa3b, v3
	v_mul_f32_e32 v144, 0xbfb8aa3b, v144
	v_mul_f32_e32 v145, 0xbfb8aa3b, v145
	v_mul_f32_e32 v149, 0xbfb8aa3b, v149
	v_mul_f32_e32 v147, 0xbfb8aa3b, v147
	v_exp_f32_e32 v2, v2
	v_exp_f32_e32 v3, v3
	v_exp_f32_e32 v144, v144
	v_exp_f32_e32 v145, v145
	v_add_f32_e32 v146, 1.0, v148
	v_add_f32_e32 v148, 1.0, v150
	v_exp_f32_e32 v149, v149
	v_exp_f32_e32 v150, v147
	v_add_f32_e32 v2, 1.0, v2
	v_add_f32_e32 v3, 1.0, v3
	v_add_f32_e32 v144, 1.0, v144
	v_add_f32_e32 v145, 1.0, v145
	v_rcp_f32_e32 v147, v148
	v_add_f32_e32 v148, 1.0, v149
	v_add_f32_e32 v149, 1.0, v150
	v_rcp_f32_e32 v2, v2
	v_rcp_f32_e32 v3, v3
	v_rcp_f32_e32 v144, v144
	v_rcp_f32_e32 v145, v145
	v_rcp_f32_e32 v146, v146
	v_rcp_f32_e32 v148, v148
	v_rcp_f32_e32 v149, v149
	v_pk_mul_f32 v[2:3], v[48:49], v[2:3]
	v_pk_mul_f32 v[150:151], v[50:51], v[144:145]
	v_pk_mul_f32 v[146:147], v[44:45], v[146:147]
	v_pk_mul_f32 v[148:149], v[46:47], v[148:149]
	v_add_u32_e32 v169, 0x50000, v0
	v_cvt_pk_bf16_f32 v144, v2, v3
	v_cvt_pk_bf16_f32 v145, v150, v151
	v_cvt_pk_bf16_f32 v146, v146, v147
	v_cvt_pk_bf16_f32 v147, v148, v149
	global_store_dwordx4 v169, v[144:147], s[4:5]
	v_lshlrev_b32_e32 v2, 16, v140
	v_and_b32_e32 v3, 0xffff0000, v140
	v_lshlrev_b32_e32 v144, 16, v142
	v_and_b32_e32 v142, 0xffff0000, v142
	v_mul_f32_e32 v144, 0xbfb8aa3b, v144
	v_mul_f32_e32 v142, 0xbfb8aa3b, v142
	v_exp_f32_e32 v144, v144
	v_exp_f32_e32 v146, v142
	v_lshlrev_b32_e32 v140, 16, v141
	v_and_b32_e32 v141, 0xffff0000, v141
	v_lshlrev_b32_e32 v145, 16, v143
	v_and_b32_e32 v143, 0xffff0000, v143
	v_mul_f32_e32 v2, 0xbfb8aa3b, v2
	v_mul_f32_e32 v3, 0xbfb8aa3b, v3
	v_mul_f32_e32 v140, 0xbfb8aa3b, v140
	v_mul_f32_e32 v141, 0xbfb8aa3b, v141
	v_mul_f32_e32 v145, 0xbfb8aa3b, v145
	v_mul_f32_e32 v143, 0xbfb8aa3b, v143
	v_exp_f32_e32 v2, v2
	v_exp_f32_e32 v3, v3
	v_exp_f32_e32 v140, v140
	v_exp_f32_e32 v141, v141
	v_add_f32_e32 v142, 1.0, v144
	v_add_f32_e32 v144, 1.0, v146
	v_exp_f32_e32 v145, v145
	v_exp_f32_e32 v146, v143
	v_add_f32_e32 v2, 1.0, v2
	v_add_f32_e32 v3, 1.0, v3
	v_add_f32_e32 v140, 1.0, v140
	v_add_f32_e32 v141, 1.0, v141
	v_rcp_f32_e32 v143, v144
	v_add_f32_e32 v144, 1.0, v145
	v_add_f32_e32 v145, 1.0, v146
	v_rcp_f32_e32 v2, v2
	v_rcp_f32_e32 v3, v3
	v_rcp_f32_e32 v140, v140
	v_rcp_f32_e32 v141, v141
	v_rcp_f32_e32 v142, v142
	v_rcp_f32_e32 v144, v144
	v_rcp_f32_e32 v145, v145
; __device__ __forceinline__ float sigmoidf_(float x) { return __builtin_amdgcn_rcpf(1.0f + __expf(-x)); }
;     __device__ __forceinline__ void operator()(f32x4 (&acc)[2][2][4][2], const pg8::Unit& u, int wr, int wc, int fr, int fq) const {
;     ...
;             for (int m = 0; m < 4; ++m)
; #pragma unroll
;                 for (int bj = 0; bj < 2; ++bj) ga[m][bj] = __builtin_nontemporal_load((const u32x4*)((const char*)Gt + (goff + (unsigned)(ai * 128 + m * 16) * 4096u + 256u * bj)));
; #pragma unroll
;             for (int m = 0; m < 4; ++m) {
;                 const unsigned rm = moff + (unsigned)(ai * 128 + m * 16) * 2048u;
; #pragma unroll
;                 for (int bj = 0; bj < 2; ++bj) {
;                     float fa[8], o[8]; unpack8(ga[m][bj], fa);
; #pragma unroll
;                     for (int e = 0; e < 8; ++e) o[e] = sigmoidf_(fa[e]) * acc[ai][bj][m][e >> 2][e & 3];
;                     *(u32x4*)((char*)MG + (rm + 256u * bj)) = pack8(o);
;                 }
	v_pk_mul_f32 v[2:3], v[16:17], v[2:3]
	v_pk_mul_f32 v[146:147], v[18:19], v[140:141]
	v_pk_mul_f32 v[142:143], v[12:13], v[142:143]
	v_pk_mul_f32 v[144:145], v[14:15], v[144:145]
	v_cvt_pk_bf16_f32 v140, v2, v3
	v_cvt_pk_bf16_f32 v141, v146, v147
	v_cvt_pk_bf16_f32 v142, v142, v143
	v_cvt_pk_bf16_f32 v143, v144, v145
	v_add_u32_e32 v2, 0x50100, v0
	global_store_dwordx4 v2, v[140:143], s[4:5]
	v_lshlrev_b32_e32 v2, 16, v136
	v_and_b32_e32 v3, 0xffff0000, v136
	v_lshlrev_b32_e32 v140, 16, v138
	v_and_b32_e32 v138, 0xffff0000, v138
	v_mul_f32_e32 v140, 0xbfb8aa3b, v140
	v_mul_f32_e32 v138, 0xbfb8aa3b, v138
	v_exp_f32_e32 v140, v140
	v_exp_f32_e32 v142, v138
	v_lshlrev_b32_e32 v136, 16, v137
	v_and_b32_e32 v137, 0xffff0000, v137
	v_lshlrev_b32_e32 v141, 16, v139
	v_and_b32_e32 v139, 0xffff0000, v139
	v_mul_f32_e32 v2, 0xbfb8aa3b, v2
	v_mul_f32_e32 v3, 0xbfb8aa3b, v3
	v_mul_f32_e32 v136, 0xbfb8aa3b, v136
	v_mul_f32_e32 v137, 0xbfb8aa3b, v137
	v_mul_f32_e32 v141, 0xbfb8aa3b, v141
	v_mul_f32_e32 v139, 0xbfb8aa3b, v139
	v_exp_f32_e32 v2, v2
	v_exp_f32_e32 v3, v3
	v_exp_f32_e32 v136, v136
	v_exp_f32_e32 v137, v137
	v_add_f32_e32 v138, 1.0, v140
	v_add_f32_e32 v140, 1.0, v142
	v_exp_f32_e32 v141, v141
	v_exp_f32_e32 v142, v139
	v_add_f32_e32 v2, 1.0, v2
	v_add_f32_e32 v3, 1.0, v3
	v_add_f32_e32 v136, 1.0, v136
	v_add_f32_e32 v137, 1.0, v137
	v_rcp_f32_e32 v139, v140
	v_add_f32_e32 v140, 1.0, v141
	v_add_f32_e32 v141, 1.0, v142
	v_rcp_f32_e32 v2, v2
	v_rcp_f32_e32 v3, v3
	v_rcp_f32_e32 v136, v136
	v_rcp_f32_e32 v137, v137
	v_rcp_f32_e32 v138, v138
	v_rcp_f32_e32 v140, v140
	v_rcp_f32_e32 v141, v141
	v_pk_mul_f32 v[2:3], v[40:41], v[2:3]
	v_pk_mul_f32 v[142:143], v[42:43], v[136:137]
	v_pk_mul_f32 v[138:139], v[36:37], v[138:139]
	v_pk_mul_f32 v[140:141], v[38:39], v[140:141]
	v_add_u32_e32 v144, 0x58000, v0
	v_cvt_pk_bf16_f32 v136, v2, v3
	v_cvt_pk_bf16_f32 v137, v142, v143
	v_cvt_pk_bf16_f32 v138, v138, v139
	v_cvt_pk_bf16_f32 v139, v140, v141
	global_store_dwordx4 v144, v[136:139], s[4:5]
	v_lshlrev_b32_e32 v2, 16, v132
	v_and_b32_e32 v3, 0xffff0000, v132
	v_lshlrev_b32_e32 v136, 16, v134
	v_and_b32_e32 v134, 0xffff0000, v134
	v_mul_f32_e32 v136, 0xbfb8aa3b, v136
	v_mul_f32_e32 v134, 0xbfb8aa3b, v134
	v_exp_f32_e32 v136, v136
	v_exp_f32_e32 v138, v134
	v_lshlrev_b32_e32 v132, 16, v133
	v_and_b32_e32 v133, 0xffff0000, v133
	v_lshlrev_b32_e32 v137, 16, v135
	v_and_b32_e32 v135, 0xffff0000, v135
	v_mul_f32_e32 v2, 0xbfb8aa3b, v2
	v_mul_f32_e32 v3, 0xbfb8aa3b, v3
	v_mul_f32_e32 v132, 0xbfb8aa3b, v132
	v_mul_f32_e32 v133, 0xbfb8aa3b, v133
	v_mul_f32_e32 v137, 0xbfb8aa3b, v137
	v_mul_f32_e32 v135, 0xbfb8aa3b, v135
	v_exp_f32_e32 v2, v2
	v_exp_f32_e32 v3, v3
	v_exp_f32_e32 v132, v132
	v_exp_f32_e32 v133, v133
	v_add_f32_e32 v134, 1.0, v136
	v_add_f32_e32 v136, 1.0, v138
	v_exp_f32_e32 v137, v137
	v_exp_f32_e32 v138, v135
	v_add_f32_e32 v2, 1.0, v2
	v_add_f32_e32 v3, 1.0, v3
	v_add_f32_e32 v132, 1.0, v132
	v_add_f32_e32 v133, 1.0, v133
	v_rcp_f32_e32 v135, v136
	v_add_f32_e32 v136, 1.0, v137
	v_add_f32_e32 v137, 1.0, v138
	v_rcp_f32_e32 v2, v2
	v_rcp_f32_e32 v3, v3
	v_rcp_f32_e32 v132, v132
	v_rcp_f32_e32 v133, v133
	v_rcp_f32_e32 v134, v134
	v_rcp_f32_e32 v136, v136
	v_rcp_f32_e32 v137, v137
	v_pk_mul_f32 v[2:3], v[8:9], v[2:3]
	v_pk_mul_f32 v[138:139], v[10:11], v[132:133]
	v_pk_mul_f32 v[134:135], v[4:5], v[134:135]
	v_pk_mul_f32 v[136:137], v[6:7], v[136:137]
	v_cvt_pk_bf16_f32 v132, v2, v3
	v_cvt_pk_bf16_f32 v133, v138, v139
	v_cvt_pk_bf16_f32 v134, v134, v135
	v_cvt_pk_bf16_f32 v135, v136, v137
	v_add_u32_e32 v0, 0x58100, v0
	global_store_dwordx4 v0, v[132:135], s[4:5]
